# EpiMix batched loads + scan loops (delta, GLA): LDS fragment reads issued ahead of the MFMAs with counted lgkmcnt waits
# baseline (speedup 1.0000x reference)
; __device__ __forceinline__ unsigned pk2(float lo, float hi) { f32x2_t v = {lo, hi}; bf16x2_t b = __builtin_convertvector(v, bf16x2_t); return __builtin_bit_cast(unsigned, b); }
; #define LAS __attribute__((address_space(3)))
; __device__ __forceinline__ f32x16 mma32(bf16x8 a, bf16x8 b, f32x16 c) { return __builtin_amdgcn_mfma_f32_32x32x16_bf16(a, b, c, 0, 0, 0); }
; #define LDS_WAIT() asm volatile("s_waitcnt lgkmcnt(0)" ::: "memory")
; #define VM_WAIT_N(n) asm volatile("s_waitcnt vmcnt(" #n ")" ::: "memory")
; __device__ __forceinline__ void delta_scan_task(const P& p, int l, int s, int h, int sl, LAS unsigned char* ldsw, int lane) {
;     ...
;         const float dec = __builtin_bit_cast(float, __builtin_amdgcn_readlane(__builtin_bit_cast(int, dec_all), n));
;         if (SCAN_LOADERS) { LDS_WAIT(); lds_wait_ge(FL + 0, (unsigned)n + 1u, FL + 5); lds_wait_ge(FL + 1, (unsigned)n + 1u, FL + 5); }
;         else { VM_WAIT_N(24); LDS_WAIT(); }
;         f32x16 u[2], o[2];
; #pragma unroll
;         for (int ti = 0; ti < 2; ++ti) {
; #pragma unroll
;             for (int g = 0; g < 4; ++g) { const f32x4v ub4 = FRAGF4(bufA, 32 + ti * 4 + g, lane); u[ti][4 * g] = ub4.x; u[ti][4 * g + 1] = ub4.y; u[ti][4 * g + 2] = ub4.z; u[ti][4 * g + 3] = ub4.w; }
;             o[ti] = zero16();
; #pragma unroll
;             for (int ks = 0; ks < 8; ++ks) {
;                 const bf16x8 b = *(const LAS bf16x8*)(ST + r * 136 + 16 * ks + 8 * hh);
;                 u[ti] = mma32(FRAG16(bufA, ti * 8 + ks, lane), b, u[ti]); o[ti] = mma32(FRAG16(bufA, 16 + ti * 8 + ks, lane), b, o[ti]);
;             }
;         }
; #pragma unroll
;         for (int ti = 0; ti < 2; ++ti)
; #pragma unroll
;             for (int g = 0; g < 4; ++g) { u32x2v w; w.x = pk2(u[ti][4 * g], u[ti][4 * g + 1]); w.y = pk2(u[ti][4 * g + 2], u[ti][4 * g + 3]); *(LAS u32x2v*)(UT + r * 72 + 32 * ti + 8 * g + 4 * hh) = w; }
;         LDS_WAIT();
;         if (SCAN_LOADERS) { if (lane == 0) FL[3] = (unsigned)n + 1u; lds_wait_ge(FL + 2, (unsigned)n + 1u, FL + 5); }
.LBB0_1502:
	s_waitcnt lgkmcnt(0)
	v_add_u32_e32 v172, v194, v148
	s_add_i32 s34, s7, 1
	ds_read_b128 v[98:101], v209 offset:49152
	ds_read_b128 v[102:105], v209 offset:50176
	ds_read_b128 v[106:109], v209 offset:51200
	ds_read_b128 v[110:113], v209 offset:52224
	ds_read_b128 v[70:73], v172
	ds_read_b128 v[236:239], v209 offset:16384
	ds_read_b128 v[240:243], v209 offset:32768
	ds_read_b128 v[130:133], v172 offset:32
	ds_read_b128 v[244:247], v209 offset:17408
	ds_read_b128 v[168:171], v209 offset:33792
	ds_read_b128 v[212:215], v172 offset:64
	ds_read_b128 v[232:235], v209 offset:18432
	s_waitcnt lgkmcnt(6)
	v_mfma_f32_32x32x16_bf16 v[98:113], v[236:239], v[70:73], v[98:113]
	ds_read_b128 v[66:69], v209 offset:34816
	s_waitcnt lgkmcnt(6)
	v_mfma_f32_32x32x16_bf16 v[82:97], v[240:243], v[70:73], 0
	ds_read_b128 v[134:137], v172 offset:96
	ds_read_b128 v[236:239], v209 offset:19456
	s_waitcnt lgkmcnt(6)
	v_mfma_f32_32x32x16_bf16 v[98:113], v[244:247], v[130:133], v[98:113]
	ds_read_b128 v[240:243], v209 offset:35840
	s_waitcnt lgkmcnt(6)
	v_mfma_f32_32x32x16_bf16 v[82:97], v[168:171], v[130:133], v[82:97]
	ds_read_b128 v[216:219], v172 offset:128
	ds_read_b128 v[244:247], v209 offset:20480
	s_waitcnt lgkmcnt(6)
	v_mfma_f32_32x32x16_bf16 v[98:113], v[232:235], v[212:215], v[98:113]
	ds_read_b128 v[168:171], v209 offset:36864
	s_waitcnt lgkmcnt(6)
	v_mfma_f32_32x32x16_bf16 v[82:97], v[66:69], v[212:215], v[82:97]
	ds_read_b128 v[220:223], v172 offset:160
	ds_read_b128 v[232:235], v209 offset:21504
	s_waitcnt lgkmcnt(6)
	v_mfma_f32_32x32x16_bf16 v[98:113], v[236:239], v[134:137], v[98:113]
	ds_read_b128 v[66:69], v209 offset:37888
	s_waitcnt lgkmcnt(6)
	v_mfma_f32_32x32x16_bf16 v[82:97], v[240:243], v[134:137], v[82:97]
	ds_read_b128 v[224:227], v172 offset:192
	ds_read_b128 v[236:239], v209 offset:22528
	s_waitcnt lgkmcnt(6)
	v_mfma_f32_32x32x16_bf16 v[98:113], v[244:247], v[216:219], v[98:113]
	ds_read_b128 v[240:243], v209 offset:38912
	s_waitcnt lgkmcnt(6)
	v_mfma_f32_32x32x16_bf16 v[82:97], v[168:171], v[216:219], v[82:97]
	ds_read_b128 v[228:231], v172 offset:224
	ds_read_b128 v[244:247], v209 offset:23552
	s_waitcnt lgkmcnt(6)
	v_mfma_f32_32x32x16_bf16 v[98:113], v[232:235], v[220:223], v[98:113]
	ds_read_b128 v[168:171], v209 offset:39936
	s_waitcnt lgkmcnt(6)
	v_mfma_f32_32x32x16_bf16 v[82:97], v[66:69], v[220:223], v[82:97]
	s_waitcnt lgkmcnt(4)
	v_mfma_f32_32x32x16_bf16 v[98:113], v[236:239], v[224:227], v[98:113]
	s_waitcnt lgkmcnt(3)
	v_mfma_f32_32x32x16_bf16 v[82:97], v[240:243], v[224:227], v[82:97]
	s_waitcnt lgkmcnt(1)
	v_mfma_f32_32x32x16_bf16 v[98:113], v[244:247], v[228:231], v[98:113]
	s_waitcnt lgkmcnt(0)
	v_mfma_f32_32x32x16_bf16 v[82:97], v[168:171], v[228:231], v[82:97]
	ds_read_b128 v[114:117], v209 offset:53248
	ds_read_b128 v[118:121], v209 offset:54272
	ds_read_b128 v[122:125], v209 offset:55296
	ds_read_b128 v[126:129], v209 offset:56320
	ds_read_b128 v[236:239], v209 offset:24576
	ds_read_b128 v[240:243], v209 offset:40960
	ds_read_b128 v[244:247], v209 offset:25600
	ds_read_b128 v[168:171], v209 offset:41984
	ds_read_b128 v[232:235], v209 offset:26624
	s_waitcnt lgkmcnt(4)
	v_mfma_f32_32x32x16_bf16 v[114:129], v[236:239], v[70:73], v[114:129]
	ds_read_b128 v[236:239], v209 offset:43008
	s_waitcnt lgkmcnt(4)
	v_mfma_f32_32x32x16_bf16 v[66:81], v[240:243], v[70:73], 0
	ds_read_b128 v[240:243], v209 offset:27648
	s_waitcnt lgkmcnt(4)
	v_mfma_f32_32x32x16_bf16 v[114:129], v[244:247], v[130:133], v[114:129]
	ds_read_b128 v[244:247], v209 offset:44032
	s_waitcnt lgkmcnt(4)
	v_mfma_f32_32x32x16_bf16 v[66:81], v[168:171], v[130:133], v[66:81]
	ds_read_b128 v[168:171], v209 offset:28672
	s_waitcnt lgkmcnt(4)
	v_mfma_f32_32x32x16_bf16 v[114:129], v[232:235], v[212:215], v[114:129]
	ds_read_b128 v[232:235], v209 offset:45056
	s_waitcnt lgkmcnt(4)
	v_mfma_f32_32x32x16_bf16 v[66:81], v[236:239], v[212:215], v[66:81]
	ds_read_b128 v[236:239], v209 offset:29696
	s_waitcnt lgkmcnt(4)
	v_mfma_f32_32x32x16_bf16 v[114:129], v[240:243], v[134:137], v[114:129]
	ds_read_b128 v[240:243], v209 offset:46080
	s_waitcnt lgkmcnt(4)
	v_mfma_f32_32x32x16_bf16 v[66:81], v[244:247], v[134:137], v[66:81]
	ds_read_b128 v[244:247], v209 offset:30720
	s_waitcnt lgkmcnt(4)
	v_mfma_f32_32x32x16_bf16 v[114:129], v[168:171], v[216:219], v[114:129]
	ds_read_b128 v[168:171], v209 offset:47104
	s_waitcnt lgkmcnt(4)
	v_mfma_f32_32x32x16_bf16 v[66:81], v[232:235], v[216:219], v[66:81]
	ds_read_b128 v[232:235], v209 offset:31744
	s_waitcnt lgkmcnt(4)
	v_mfma_f32_32x32x16_bf16 v[114:129], v[236:239], v[220:223], v[114:129]
	ds_read_b128 v[236:239], v209 offset:48128
	s_waitcnt lgkmcnt(4)
	v_mfma_f32_32x32x16_bf16 v[66:81], v[240:243], v[220:223], v[66:81]
	s_waitcnt lgkmcnt(3)
	v_mfma_f32_32x32x16_bf16 v[114:129], v[244:247], v[224:227], v[114:129]
	s_waitcnt lgkmcnt(2)
	v_mfma_f32_32x32x16_bf16 v[66:81], v[168:171], v[224:227], v[66:81]
	s_waitcnt lgkmcnt(1)
	v_mfma_f32_32x32x16_bf16 v[114:129], v[232:235], v[228:231], v[114:129]
	s_waitcnt lgkmcnt(0)
	v_mfma_f32_32x32x16_bf16 v[66:81], v[236:239], v[228:231], v[66:81]
	s_nop 7
	s_nop 7
	v_add_u32_e32 v130, v195, v140
	v_add_u32_e32 v131, 0x2000, v130
	v_cvt_pk_bf16_f32 v236, v98, v99
	v_cvt_pk_bf16_f32 v237, v100, v101
	v_cvt_pk_bf16_f32 v238, v102, v103
	v_cvt_pk_bf16_f32 v239, v104, v105
	ds_write2_b64 v131, v[236:237], v[238:239] offset0:64 offset1:66
	v_cvt_pk_bf16_f32 v240, v106, v107
	v_cvt_pk_bf16_f32 v241, v108, v109
	v_cvt_pk_bf16_f32 v242, v110, v111
	v_cvt_pk_bf16_f32 v243, v112, v113
	ds_write2_b64 v131, v[240:241], v[242:243] offset0:68 offset1:70
	v_cvt_pk_bf16_f32 v236, v114, v115
	v_cvt_pk_bf16_f32 v237, v116, v117
	v_cvt_pk_bf16_f32 v238, v118, v119
	v_cvt_pk_bf16_f32 v239, v120, v121
	ds_write2_b64 v131, v[236:237], v[238:239] offset0:72 offset1:74
	v_cvt_pk_bf16_f32 v240, v122, v123
	v_cvt_pk_bf16_f32 v241, v124, v125
	v_cvt_pk_bf16_f32 v242, v126, v127
	v_cvt_pk_bf16_f32 v243, v128, v129
	ds_write2_b64 v131, v[240:241], v[242:243] offset0:76 offset1:78
	s_waitcnt lgkmcnt(0)
	s_and_saveexec_b64 s[8:9], s[0:1]
	v_mov_b32_e32 v98, s34
	ds_write_b32 v163, v98 offset:13324
	s_or_b64 exec, exec, s[8:9]
	ds_read_b32 v98, v163 offset:13320
	s_waitcnt lgkmcnt(0)
	v_cmp_lt_u32_e32 vcc, s7, v98
	s_cbranch_vccnz .LBB0_1515
	s_mov_b32 s4, 1
	s_branch .LBB0_1507

; #define LAS __attribute__((address_space(3)))
; __device__ __forceinline__ f32x16 mma32(bf16x8 a, bf16x8 b, f32x16 c) { return __builtin_amdgcn_mfma_f32_32x32x16_bf16(a, b, c, 0, 0, 0); }
; __device__ __forceinline__ int acc_row(int reg, int hh) { return (reg & 3) + 8 * (reg >> 2) + 4 * hh; }
; __device__ __forceinline__ void delta_scan_task(const P& p, int l, int s, int h, int sl, LAS unsigned char* ldsw, int lane) {
;     ...
;         bf16x8 ub[4];
; #pragma unroll
;         for (int ks = 0; ks < 4; ++ks) ub[ks] = *(const LAS bf16x8*)(UT + r * 72 + 16 * ks + 8 * hh);
; #pragma unroll
;         for (int ti = 0; ti < 2; ++ti) {
; #pragma unroll
;             for (int ks = 0; ks < 4; ++ks) o[ti] = mma32(FRAG16(bufB, ti * 4 + ks, lane), ub[ks], o[ti]);
; #pragma unroll
;             for (int reg = 0; reg < 16; ++reg) p.OCRAW[(size_t)(r0 + 32 * ti + acc_row(reg, hh)) * 1024 + h * 128 + 32 * sl + r] = o[ti][reg];
;         }
; #pragma unroll
;         for (int d = 0; d < 4; ++d) {
; #pragma unroll
;             for (int reg = 0; reg < 16; ++reg) S[d][reg] *= dec;
; #pragma unroll
;             for (int ks = 0; ks < 4; ++ks) S[d] = mma32(FRAG16(bufB, 8 + d * 4 + ks, lane), ub[ks], S[d]);
;         }
.LBB0_1515:
	s_waitcnt lgkmcnt(0)
	v_add_u32_e32 v172, v195, v148
	v_lshl_add_u32 v162, s7, 18, v149
	ds_read_b128 v[110:113], v172 offset:8704
	ds_read_b128 v[106:109], v172 offset:8736
	ds_read_b128 v[102:105], v172 offset:8768
	ds_read_b128 v[98:101], v172 offset:8800
	ds_read_b128 v[236:239], v209 offset:57344
	ds_read_b128 v[240:243], v209 offset:58368
	ds_read_b128 v[244:247], v209 offset:59392
	ds_read_b128 v[168:171], v209 offset:60416
	ds_read_b128 v[232:235], v209 offset:61440
	ds_read_b128 v[118:121], v209 offset:62464
	s_waitcnt lgkmcnt(5)
	v_mfma_f32_32x32x16_bf16 v[82:97], v[236:239], v[110:113], v[82:97]
	v_mul_f32_e64 v64, v64, s6
	v_mul_f32_e64 v65, v65, s6
	v_mul_f32_e64 v62, v62, s6
	v_mul_f32_e64 v63, v63, s6
	v_pk_mul_f32 v[60:61], v[60:61], s[6:7] op_sel_hi:[1,0]
	v_pk_mul_f32 v[58:59], v[58:59], s[6:7] op_sel_hi:[1,0]
	ds_read_b128 v[122:125], v209 offset:63488
	s_waitcnt lgkmcnt(5)
	v_mfma_f32_32x32x16_bf16 v[82:97], v[240:243], v[106:109], v[82:97]
	v_pk_mul_f32 v[56:57], v[56:57], s[6:7] op_sel_hi:[1,0]
	v_pk_mul_f32 v[54:55], v[54:55], s[6:7] op_sel_hi:[1,0]
	v_mul_f32_e64 v52, v52, s6
	v_mul_f32_e64 v53, v53, s6
	v_mul_f32_e64 v50, v50, s6
	v_mul_f32_e64 v51, v51, s6
	ds_read_b128 v[126:129], v209 offset:64512
	s_waitcnt lgkmcnt(5)
	v_mfma_f32_32x32x16_bf16 v[82:97], v[244:247], v[102:105], v[82:97]
	v_pk_mul_f32 v[48:49], v[48:49], s[6:7] op_sel_hi:[1,0]
	v_pk_mul_f32 v[46:47], v[46:47], s[6:7] op_sel_hi:[1,0]
	v_pk_mul_f32 v[44:45], v[44:45], s[6:7] op_sel_hi:[1,0]
	v_pk_mul_f32 v[42:43], v[42:43], s[6:7] op_sel_hi:[1,0]
	v_mul_f32_e64 v40, v40, s6
	ds_read_b128 v[236:239], v210 offset:8192
	s_waitcnt lgkmcnt(5)
	v_mfma_f32_32x32x16_bf16 v[82:97], v[168:171], v[98:101], v[82:97]
	v_mul_f32_e64 v41, v41, s6
	v_mul_f32_e64 v38, v38, s6
	v_mul_f32_e64 v39, v39, s6
	v_pk_mul_f32 v[36:37], v[36:37], s[6:7] op_sel_hi:[1,0]
	v_pk_mul_f32 v[34:35], v[34:35], s[6:7] op_sel_hi:[1,0]
	ds_read_b128 v[240:243], v210 offset:9216
	s_waitcnt lgkmcnt(5)
	v_mfma_f32_32x32x16_bf16 v[66:81], v[232:235], v[110:113], v[66:81]
	v_pk_mul_f32 v[32:33], v[32:33], s[6:7] op_sel_hi:[1,0]
	v_pk_mul_f32 v[30:31], v[30:31], s[6:7] op_sel_hi:[1,0]
	v_mul_f32_e64 v28, v28, s6
	v_mul_f32_e64 v29, v29, s6
	v_mul_f32_e64 v26, v26, s6
	ds_read_b128 v[244:247], v210 offset:10240
	s_waitcnt lgkmcnt(5)
	v_mfma_f32_32x32x16_bf16 v[66:81], v[118:121], v[106:109], v[66:81]
	v_mul_f32_e64 v27, v27, s6
	v_pk_mul_f32 v[24:25], v[24:25], s[6:7] op_sel_hi:[1,0]
	v_pk_mul_f32 v[22:23], v[22:23], s[6:7] op_sel_hi:[1,0]
	v_pk_mul_f32 v[20:21], v[20:21], s[6:7] op_sel_hi:[1,0]
	v_pk_mul_f32 v[18:19], v[18:19], s[6:7] op_sel_hi:[1,0]
	ds_read_b128 v[168:171], v210 offset:11264
	s_waitcnt lgkmcnt(5)
	v_mfma_f32_32x32x16_bf16 v[66:81], v[122:125], v[102:105], v[66:81]
	v_pk_mul_f32 v[16:17], v[16:17], s[6:7] op_sel_hi:[1,0]
	v_pk_mul_f32 v[14:15], v[14:15], s[6:7] op_sel_hi:[1,0]
	v_pk_mul_f32 v[12:13], v[12:13], s[6:7] op_sel_hi:[1,0]
	v_mul_f32_e64 v10, v10, s6
	v_mul_f32_e64 v11, v11, s6
	ds_read_b128 v[232:235], v210 offset:12288
	s_waitcnt lgkmcnt(5)
	v_mfma_f32_32x32x16_bf16 v[66:81], v[126:129], v[98:101], v[66:81]
	v_mul_f32_e64 v8, v8, s6
	v_mul_f32_e64 v9, v9, s6
	v_pk_mul_f32 v[6:7], v[6:7], s[6:7] op_sel_hi:[1,0]
	v_pk_mul_f32 v[4:5], v[4:5], s[6:7] op_sel_hi:[1,0]
	v_pk_mul_f32 v[2:3], v[2:3], s[6:7] op_sel_hi:[1,0]
	ds_read_b128 v[118:121], v210 offset:13312
	s_waitcnt lgkmcnt(5)
	v_mfma_f32_32x32x16_bf16 v[50:65], v[236:239], v[110:113], v[50:65]
	ds_read_b128 v[122:125], v210 offset:14336
	s_waitcnt lgkmcnt(5)
	v_mfma_f32_32x32x16_bf16 v[50:65], v[240:243], v[106:109], v[50:65]
	ds_read_b128 v[126:129], v210 offset:15360
	s_waitcnt lgkmcnt(5)
	v_mfma_f32_32x32x16_bf16 v[50:65], v[244:247], v[102:105], v[50:65]
	ds_read_b128 v[236:239], v210 offset:16384
	s_waitcnt lgkmcnt(5)
; __device__ __forceinline__ f32x16 mma32(bf16x8 a, bf16x8 b, f32x16 c) { return __builtin_amdgcn_mfma_f32_32x32x16_bf16(a, b, c, 0, 0, 0); }
; __device__ __forceinline__ int acc_row(int reg, int hh) { return (reg & 3) + 8 * (reg >> 2) + 4 * hh; }
; #define LDS_WAIT() asm volatile("s_waitcnt lgkmcnt(0)" ::: "memory")
; __device__ __forceinline__ void delta_scan_task(const P& p, int l, int s, int h, int sl, LAS unsigned char* ldsw, int lane) {
;     ...
;             for (int ks = 0; ks < 4; ++ks) o[ti] = mma32(FRAG16(bufB, ti * 4 + ks, lane), ub[ks], o[ti]);
; #pragma unroll
;             for (int reg = 0; reg < 16; ++reg) p.OCRAW[(size_t)(r0 + 32 * ti + acc_row(reg, hh)) * 1024 + h * 128 + 32 * sl + r] = o[ti][reg];
;         }
; #pragma unroll
;         for (int d = 0; d < 4; ++d) {
; #pragma unroll
;             for (int reg = 0; reg < 16; ++reg) S[d][reg] *= dec;
; #pragma unroll
;             for (int ks = 0; ks < 4; ++ks) S[d] = mma32(FRAG16(bufB, 8 + d * 4 + ks, lane), ub[ks], S[d]);
;         }
;         LDS_WAIT();
;         if (SCAN_LOADERS) { if (lane == 0) FL[4] = (unsigned)n + 1u; } else delta_issue_B(p, chn, bufB, r, hh);
	v_mfma_f32_32x32x16_bf16 v[50:65], v[168:171], v[98:101], v[50:65]
	s_nop 7
	s_mov_b32 s4, 0x9000
	v_lshl_add_u64 v[114:115], v[192:193], 0, v[162:163]
	s_nop 2
	global_store_dword v[114:115], v82, off
	v_ashrrev_i32_e32 v115, 31, v162
	v_mov_b32_e32 v114, v162
	v_lshl_add_u64 v[114:115], v[192:193], 0, v[114:115]
	v_add_co_u32_e32 v116, vcc, s57, v114
	s_nop 0
	v_addc_co_u32_e32 v117, vcc, 0, v115, vcc
	v_add_co_u32_e32 v82, vcc, s97, v114
	global_store_dword v[116:117], v83, off offset:-4096
	global_store_dword v[116:117], v84, off
	v_addc_co_u32_e32 v83, vcc, 0, v115, vcc
	global_store_dword v[82:83], v85, off
	v_add_co_u32_e32 v82, vcc, s4, v114
	s_mov_b32 s4, 0x11000
	s_nop 0
	v_addc_co_u32_e32 v83, vcc, 0, v115, vcc
	global_store_dword v[82:83], v86, off offset:-4096
	global_store_dword v[82:83], v87, off
	v_add_co_u32_e32 v82, vcc, s96, v114
	s_nop 0
	v_addc_co_u32_e32 v83, vcc, 0, v115, vcc
	global_store_dword v[82:83], v88, off offset:-4096
	global_store_dword v[82:83], v89, off
	v_add_co_u32_e32 v82, vcc, s4, v114
	s_mov_b32 s4, 0x13000
	s_nop 0
	v_addc_co_u32_e32 v83, vcc, 0, v115, vcc
	global_store_dword v[82:83], v90, off offset:-4096
	global_store_dword v[82:83], v91, off
	v_add_co_u32_e32 v82, vcc, s4, v114
	s_mov_b32 s4, 0x19000
	s_nop 0
	v_addc_co_u32_e32 v83, vcc, 0, v115, vcc
	global_store_dword v[82:83], v92, off offset:-4096
	global_store_dword v[82:83], v93, off
	v_add_co_u32_e32 v82, vcc, s4, v114
	s_mov_b32 s4, 0x21000
	s_nop 0
	v_addc_co_u32_e32 v83, vcc, 0, v115, vcc
	global_store_dword v[82:83], v94, off offset:-4096
	global_store_dword v[82:83], v95, off
	v_add_co_u32_e32 v82, vcc, s16, v114
	s_nop 0
	v_addc_co_u32_e32 v83, vcc, 0, v115, vcc
	global_store_dword v[82:83], v96, off offset:-4096
	global_store_dword v[82:83], v97, off
	ds_read_b128 v[240:243], v210 offset:17408
	s_waitcnt lgkmcnt(5)
	v_mfma_f32_32x32x16_bf16 v[34:49], v[232:235], v[110:113], v[34:49]
	ds_read_b128 v[244:247], v210 offset:18432
	s_waitcnt lgkmcnt(5)
	v_mfma_f32_32x32x16_bf16 v[34:49], v[118:121], v[106:109], v[34:49]
	ds_read_b128 v[168:171], v210 offset:19456
	s_waitcnt lgkmcnt(5)
	v_mfma_f32_32x32x16_bf16 v[34:49], v[122:125], v[102:105], v[34:49]
	ds_read_b128 v[232:235], v210 offset:20480
	s_waitcnt lgkmcnt(5)
	v_mfma_f32_32x32x16_bf16 v[34:49], v[126:129], v[98:101], v[34:49]
	s_nop 7
	v_add_co_u32_e32 v82, vcc, s4, v114
	s_mov_b32 s4, 0x23000
	s_nop 0
	v_addc_co_u32_e32 v83, vcc, 0, v115, vcc
	s_nop 7
	global_store_dword v[82:83], v66, off offset:-4096
	global_store_dword v[82:83], v67, off
	v_add_co_u32_e32 v66, vcc, s4, v114
	s_mov_b32 s4, 0x29000
	s_nop 0
	v_addc_co_u32_e32 v67, vcc, 0, v115, vcc
	global_store_dword v[66:67], v68, off offset:-4096
	global_store_dword v[66:67], v69, off
	v_add_co_u32_e32 v66, vcc, s4, v114
	s_mov_b32 s4, 0x2b000
	s_nop 0
	v_addc_co_u32_e32 v67, vcc, 0, v115, vcc
	global_store_dword v[66:67], v70, off offset:-4096
	global_store_dword v[66:67], v71, off
	v_add_co_u32_e32 v66, vcc, s4, v114
	s_mov_b32 s4, 0x31000
	s_nop 0
	v_addc_co_u32_e32 v67, vcc, 0, v115, vcc
	global_store_dword v[66:67], v72, off offset:-4096
	global_store_dword v[66:67], v73, off
	v_add_co_u32_e32 v66, vcc, s4, v114
	s_mov_b32 s4, 0x33000
	s_nop 0
	v_addc_co_u32_e32 v67, vcc, 0, v115, vcc
	global_store_dword v[66:67], v74, off offset:-4096
	global_store_dword v[66:67], v75, off
	v_add_co_u32_e32 v66, vcc, s4, v114
	s_mov_b32 s4, 0x39000
	s_nop 0
	v_addc_co_u32_e32 v67, vcc, 0, v115, vcc
	global_store_dword v[66:67], v76, off offset:-4096
	global_store_dword v[66:67], v77, off
	v_add_co_u32_e32 v66, vcc, s4, v114
	s_mov_b32 s4, 0x3b000
	s_nop 0
	v_addc_co_u32_e32 v67, vcc, 0, v115, vcc
	global_store_dword v[66:67], v78, off offset:-4096
	global_store_dword v[66:67], v79, off
	v_add_co_u32_e32 v66, vcc, s4, v114
	s_nop 1
	v_addc_co_u32_e32 v67, vcc, 0, v115, vcc
	global_store_dword v[66:67], v80, off offset:-4096
	global_store_dword v[66:67], v81, off
	ds_read_b128 v[118:121], v210 offset:21504
	s_waitcnt lgkmcnt(5)
	v_mfma_f32_32x32x16_bf16 v[18:33], v[236:239], v[110:113], v[18:33]
	ds_read_b128 v[122:125], v210 offset:22528
	s_waitcnt lgkmcnt(5)
	v_mfma_f32_32x32x16_bf16 v[18:33], v[240:243], v[106:109], v[18:33]
	ds_read_b128 v[126:129], v210 offset:23552
	s_waitcnt lgkmcnt(5)
	v_mfma_f32_32x32x16_bf16 v[18:33], v[244:247], v[102:105], v[18:33]
	s_waitcnt lgkmcnt(4)
	v_mfma_f32_32x32x16_bf16 v[18:33], v[168:171], v[98:101], v[18:33]
	s_waitcnt lgkmcnt(3)
	v_mfma_f32_32x32x16_bf16 v[2:17], v[232:235], v[110:113], v[2:17]
	s_waitcnt lgkmcnt(2)
	v_mfma_f32_32x32x16_bf16 v[2:17], v[118:121], v[106:109], v[2:17]
	s_waitcnt lgkmcnt(1)
	v_mfma_f32_32x32x16_bf16 v[2:17], v[122:125], v[102:105], v[2:17]
	s_waitcnt lgkmcnt(0)
	v_mfma_f32_32x32x16_bf16 v[2:17], v[126:129], v[98:101], v[2:17]
	s_and_saveexec_b64 s[6:7], s[0:1]
	s_cbranch_execz .LBB0_1479
	v_mov_b32_e32 v66, s34
	ds_write_b32 v163, v66 offset:13328
	s_branch .LBB0_1479

; #define LAS __attribute__((address_space(3)))
; __device__ __forceinline__ f32x16 mma32(bf16x8 a, bf16x8 b, f32x16 c) { return __builtin_amdgcn_mfma_f32_32x32x16_bf16(a, b, c, 0, 0, 0); }
; __device__ __forceinline__ int acc_row(int reg, int hh) { return (reg & 3) + 8 * (reg >> 2) + 4 * hh; }
; __device__ __forceinline__ void gla_scan_task(const P& p, int l, int s, int h, int sl, LAS unsigned char* ldsw, int lane) {
;     ...
;         bf16x8 vb[4];
; #pragma unroll
;         for (int ks = 0; ks < 4; ++ks) vb[ks] = FRAG16(bufA, ks, lane);
; #pragma unroll
;         for (int ti = 0; ti < 2; ++ti) {
;             f32x16 o = zero16();
; #pragma unroll
;             for (int ks = 0; ks < 8; ++ks) { const bf16x8 b = *(const LAS bf16x8*)(ST + r * 136 + 16 * ks + 8 * hh); o = mma32(FRAG16(bufA, 4 + ti * 8 + ks, lane), b, o); }
; #pragma unroll
;             for (int ks = 0; ks < 4; ++ks) o = mma32(FRAG16(bufA, 20 + ti * 4 + ks, lane), vb[ks], o);
; #pragma unroll
;             for (int reg = 0; reg < 16; ++reg) p.OBRAW[(size_t)(r0 + 32 * ti + acc_row(reg, hh)) * 1024 + h * 256 + 32 * sl + r] = o[reg];
.LBB0_1543:
	s_waitcnt lgkmcnt(0)
	v_add_u32_e32 v172, v194, v148
	v_lshl_add_u32 v132, s34, 6, v134
	s_add_i32 s7, s34, 1
	v_ashrrev_i32_e32 v133, 31, v132
	v_lshlrev_b64 v[136:137], 12, v[132:133]
	v_lshl_add_u64 v[136:137], v[130:131], 0, v[136:137]
	ds_read_b128 v[94:97], v209 offset:16384
	ds_read_b128 v[90:93], v209 offset:17408
	ds_read_b128 v[86:89], v209 offset:18432
	ds_read_b128 v[82:85], v209 offset:19456
	ds_read_b128 v[122:125], v172
	ds_read_b128 v[236:239], v209 offset:20480
	ds_read_b128 v[118:121], v172 offset:32
	ds_read_b128 v[240:243], v209 offset:21504
	ds_read_b128 v[126:129], v172 offset:64
	ds_read_b128 v[244:247], v209 offset:22528
	ds_read_b128 v[114:117], v172 offset:96
	ds_read_b128 v[168:171], v209 offset:23552
	ds_read_b128 v[110:113], v172 offset:128
	ds_read_b128 v[212:215], v209 offset:24576
	s_waitcnt lgkmcnt(8)
	v_mfma_f32_32x32x16_bf16 v[66:81], v[236:239], v[122:125], 0
	ds_read_b128 v[106:109], v172 offset:160
	ds_read_b128 v[216:219], v209 offset:25600
	ds_read_b128 v[102:105], v172 offset:192
	ds_read_b128 v[220:223], v209 offset:26624
	s_waitcnt lgkmcnt(10)
	v_mfma_f32_32x32x16_bf16 v[66:81], v[240:243], v[118:121], v[66:81]
	ds_read_b128 v[98:101], v172 offset:224
	ds_read_b128 v[224:227], v209 offset:27648
	s_waitcnt lgkmcnt(10)
	v_mfma_f32_32x32x16_bf16 v[66:81], v[244:247], v[126:129], v[66:81]
	ds_read_b128 v[228:231], v209 offset:36864
	s_waitcnt lgkmcnt(9)
	v_mfma_f32_32x32x16_bf16 v[66:81], v[168:171], v[114:117], v[66:81]
	ds_read_b128 v[232:235], v209 offset:37888
	s_waitcnt lgkmcnt(8)
	v_mfma_f32_32x32x16_bf16 v[66:81], v[212:215], v[110:113], v[66:81]
	ds_read_b128 v[236:239], v209 offset:38912
	s_waitcnt lgkmcnt(7)
	v_mfma_f32_32x32x16_bf16 v[66:81], v[216:219], v[106:109], v[66:81]
	ds_read_b128 v[240:243], v209 offset:39936
	s_waitcnt lgkmcnt(6)
	v_mfma_f32_32x32x16_bf16 v[66:81], v[220:223], v[102:105], v[66:81]
	s_waitcnt lgkmcnt(4)
	v_mfma_f32_32x32x16_bf16 v[66:81], v[224:227], v[98:101], v[66:81]
	s_waitcnt lgkmcnt(3)
	v_mfma_f32_32x32x16_bf16 v[66:81], v[228:231], v[94:97], v[66:81]
	s_waitcnt lgkmcnt(2)
	v_mfma_f32_32x32x16_bf16 v[66:81], v[232:235], v[90:93], v[66:81]
	s_waitcnt lgkmcnt(1)
	v_mfma_f32_32x32x16_bf16 v[66:81], v[236:239], v[86:89], v[66:81]
	s_waitcnt lgkmcnt(0)
	v_mfma_f32_32x32x16_bf16 v[66:81], v[240:243], v[82:85], v[66:81]
	s_nop 11
	global_store_dword v[136:137], v66, off
	v_or_b32_e32 v136, 1, v132
	v_ashrrev_i32_e32 v137, 31, v136
	v_lshlrev_b64 v[136:137], 12, v[136:137]
	v_lshl_add_u64 v[136:137], v[130:131], 0, v[136:137]
	v_or_b32_e32 v66, 2, v132
	global_store_dword v[136:137], v67, off
	v_ashrrev_i32_e32 v67, 31, v66
	v_lshlrev_b64 v[66:67], 12, v[66:67]
	v_lshl_add_u64 v[66:67], v[130:131], 0, v[66:67]
	global_store_dword v[66:67], v68, off
	v_or_b32_e32 v66, 3, v132
	v_ashrrev_i32_e32 v67, 31, v66
	v_lshlrev_b64 v[66:67], 12, v[66:67]
	v_lshl_add_u64 v[66:67], v[130:131], 0, v[66:67]
	global_store_dword v[66:67], v69, off
	v_or_b32_e32 v66, 8, v132
	v_ashrrev_i32_e32 v67, 31, v66
	v_lshlrev_b64 v[66:67], 12, v[66:67]
	v_lshl_add_u64 v[66:67], v[130:131], 0, v[66:67]
	global_store_dword v[66:67], v70, off
	v_or_b32_e32 v66, 9, v132
	v_ashrrev_i32_e32 v67, 31, v66
	v_lshlrev_b64 v[66:67], 12, v[66:67]
	v_lshl_add_u64 v[66:67], v[130:131], 0, v[66:67]
	global_store_dword v[66:67], v71, off
	v_or_b32_e32 v66, 10, v132
	v_ashrrev_i32_e32 v67, 31, v66
	v_lshlrev_b64 v[66:67], 12, v[66:67]
	v_lshl_add_u64 v[66:67], v[130:131], 0, v[66:67]
	global_store_dword v[66:67], v72, off
	v_or_b32_e32 v66, 11, v132
	v_ashrrev_i32_e32 v67, 31, v66
	v_lshlrev_b64 v[66:67], 12, v[66:67]
	v_lshl_add_u64 v[66:67], v[130:131], 0, v[66:67]
	global_store_dword v[66:67], v73, off
	v_or_b32_e32 v66, 16, v132
	v_ashrrev_i32_e32 v67, 31, v66
	v_lshlrev_b64 v[66:67], 12, v[66:67]
	v_lshl_add_u64 v[66:67], v[130:131], 0, v[66:67]
	global_store_dword v[66:67], v74, off
	v_or_b32_e32 v66, 17, v132
	v_ashrrev_i32_e32 v67, 31, v66
	v_lshlrev_b64 v[66:67], 12, v[66:67]
	v_lshl_add_u64 v[66:67], v[130:131], 0, v[66:67]
	global_store_dword v[66:67], v75, off
	v_or_b32_e32 v66, 18, v132
	v_ashrrev_i32_e32 v67, 31, v66
	v_lshlrev_b64 v[66:67], 12, v[66:67]
	v_lshl_add_u64 v[66:67], v[130:131], 0, v[66:67]
	global_store_dword v[66:67], v76, off
	v_or_b32_e32 v66, 19, v132
	v_ashrrev_i32_e32 v67, 31, v66
	v_lshlrev_b64 v[66:67], 12, v[66:67]
	v_lshl_add_u64 v[66:67], v[130:131], 0, v[66:67]
	global_store_dword v[66:67], v77, off
	v_or_b32_e32 v66, 24, v132
	v_ashrrev_i32_e32 v67, 31, v66
	v_lshlrev_b64 v[66:67], 12, v[66:67]
	v_lshl_add_u64 v[66:67], v[130:131], 0, v[66:67]
	global_store_dword v[66:67], v78, off
	v_or_b32_e32 v66, 25, v132
	v_ashrrev_i32_e32 v67, 31, v66
	v_lshlrev_b64 v[66:67], 12, v[66:67]
	v_lshl_add_u64 v[66:67], v[130:131], 0, v[66:67]
	global_store_dword v[66:67], v79, off
	v_or_b32_e32 v66, 26, v132
	v_ashrrev_i32_e32 v67, 31, v66
	v_lshlrev_b64 v[66:67], 12, v[66:67]
	v_lshl_add_u64 v[66:67], v[130:131], 0, v[66:67]
	global_store_dword v[66:67], v80, off
	v_or_b32_e32 v66, 27, v132
	v_ashrrev_i32_e32 v67, 31, v66
	v_lshlrev_b64 v[66:67], 12, v[66:67]
	v_lshl_add_u64 v[66:67], v[130:131], 0, v[66:67]
	global_store_dword v[66:67], v81, off
	ds_read_b128 v[236:239], v209 offset:28672
	ds_read_b128 v[240:243], v209 offset:29696
	ds_read_b128 v[244:247], v209 offset:30720
	ds_read_b128 v[168:171], v209 offset:31744
	ds_read_b128 v[212:215], v209 offset:32768
	ds_read_b128 v[216:219], v209 offset:33792
	s_waitcnt lgkmcnt(5)
; #define LAS __attribute__((address_space(3)))
; __device__ __forceinline__ f32x16 mma32(bf16x8 a, bf16x8 b, f32x16 c) { return __builtin_amdgcn_mfma_f32_32x32x16_bf16(a, b, c, 0, 0, 0); }
; __device__ __forceinline__ int acc_row(int reg, int hh) { return (reg & 3) + 8 * (reg >> 2) + 4 * hh; }
; #define LDS_WAIT() asm volatile("s_waitcnt lgkmcnt(0)" ::: "memory")
; __device__ __forceinline__ void gla_scan_task(const P& p, int l, int s, int h, int sl, LAS unsigned char* ldsw, int lane) {
;     ...
; #pragma unroll
;         for (int ti = 0; ti < 2; ++ti) {
;             f32x16 o = zero16();
; #pragma unroll
;             for (int ks = 0; ks < 8; ++ks) { const bf16x8 b = *(const LAS bf16x8*)(ST + r * 136 + 16 * ks + 8 * hh); o = mma32(FRAG16(bufA, 4 + ti * 8 + ks, lane), b, o); }
; #pragma unroll
;             for (int ks = 0; ks < 4; ++ks) o = mma32(FRAG16(bufA, 20 + ti * 4 + ks, lane), vb[ks], o);
; #pragma unroll
;             for (int reg = 0; reg < 16; ++reg) p.OBRAW[(size_t)(r0 + 32 * ti + acc_row(reg, hh)) * 1024 + h * 256 + 32 * sl + r] = o[reg];
;         }
;         LDS_WAIT();
;         if (SCAN_LOADERS) { if (lane == 0) FL[3] = (unsigned)n + 1u; lds_wait_ge(FL + 2, (unsigned)n + 1u, FL + 5); }
	v_mfma_f32_32x32x16_bf16 v[66:81], v[236:239], v[122:125], 0
	ds_read_b128 v[220:223], v209 offset:34816
	s_waitcnt lgkmcnt(5)
	v_mfma_f32_32x32x16_bf16 v[66:81], v[240:243], v[118:121], v[66:81]
	ds_read_b128 v[224:227], v209 offset:35840
	s_waitcnt lgkmcnt(5)
	v_mfma_f32_32x32x16_bf16 v[66:81], v[244:247], v[126:129], v[66:81]
	ds_read_b128 v[228:231], v209 offset:40960
	s_waitcnt lgkmcnt(5)
	v_mfma_f32_32x32x16_bf16 v[66:81], v[168:171], v[114:117], v[66:81]
	ds_read_b128 v[232:235], v209 offset:41984
	s_waitcnt lgkmcnt(5)
	v_mfma_f32_32x32x16_bf16 v[66:81], v[212:215], v[110:113], v[66:81]
	ds_read_b128 v[236:239], v209 offset:43008
	s_waitcnt lgkmcnt(5)
	v_mfma_f32_32x32x16_bf16 v[66:81], v[216:219], v[106:109], v[66:81]
	ds_read_b128 v[240:243], v209 offset:44032
	s_waitcnt lgkmcnt(5)
	v_mfma_f32_32x32x16_bf16 v[66:81], v[220:223], v[102:105], v[66:81]
	s_waitcnt lgkmcnt(4)
	v_mfma_f32_32x32x16_bf16 v[66:81], v[224:227], v[98:101], v[66:81]
	s_waitcnt lgkmcnt(3)
	v_mfma_f32_32x32x16_bf16 v[66:81], v[228:231], v[94:97], v[66:81]
	s_waitcnt lgkmcnt(2)
	v_mfma_f32_32x32x16_bf16 v[66:81], v[232:235], v[90:93], v[66:81]
	s_waitcnt lgkmcnt(1)
	v_mfma_f32_32x32x16_bf16 v[66:81], v[236:239], v[86:89], v[66:81]
	s_waitcnt lgkmcnt(0)
	v_mfma_f32_32x32x16_bf16 v[66:81], v[240:243], v[82:85], v[66:81]
	v_or_b32_e32 v98, 32, v132
	v_ashrrev_i32_e32 v99, 31, v98
	v_lshlrev_b64 v[98:99], 12, v[98:99]
	v_lshl_add_u64 v[98:99], v[130:131], 0, v[98:99]
	s_nop 7
	global_store_dword v[98:99], v66, off
	v_or_b32_e32 v98, 33, v132
	v_ashrrev_i32_e32 v99, 31, v98
	v_lshlrev_b64 v[98:99], 12, v[98:99]
	v_lshl_add_u64 v[98:99], v[130:131], 0, v[98:99]
	v_or_b32_e32 v66, 34, v132
	global_store_dword v[98:99], v67, off
	v_ashrrev_i32_e32 v67, 31, v66
	v_lshlrev_b64 v[66:67], 12, v[66:67]
	v_lshl_add_u64 v[66:67], v[130:131], 0, v[66:67]
	global_store_dword v[66:67], v68, off
	v_or_b32_e32 v66, 35, v132
	v_ashrrev_i32_e32 v67, 31, v66
	v_lshlrev_b64 v[66:67], 12, v[66:67]
	v_lshl_add_u64 v[66:67], v[130:131], 0, v[66:67]
	global_store_dword v[66:67], v69, off
	v_or_b32_e32 v66, 40, v132
	v_ashrrev_i32_e32 v67, 31, v66
	v_lshlrev_b64 v[66:67], 12, v[66:67]
	v_lshl_add_u64 v[66:67], v[130:131], 0, v[66:67]
	global_store_dword v[66:67], v70, off
	v_or_b32_e32 v66, 41, v132
	v_ashrrev_i32_e32 v67, 31, v66
	v_lshlrev_b64 v[66:67], 12, v[66:67]
	v_lshl_add_u64 v[66:67], v[130:131], 0, v[66:67]
	global_store_dword v[66:67], v71, off
	v_or_b32_e32 v66, 42, v132
	v_ashrrev_i32_e32 v67, 31, v66
	v_lshlrev_b64 v[66:67], 12, v[66:67]
	v_lshl_add_u64 v[66:67], v[130:131], 0, v[66:67]
	global_store_dword v[66:67], v72, off
	v_or_b32_e32 v66, 43, v132
	v_ashrrev_i32_e32 v67, 31, v66
	v_lshlrev_b64 v[66:67], 12, v[66:67]
	v_lshl_add_u64 v[66:67], v[130:131], 0, v[66:67]
	global_store_dword v[66:67], v73, off
	v_or_b32_e32 v66, 48, v132
	v_ashrrev_i32_e32 v67, 31, v66
	v_lshlrev_b64 v[66:67], 12, v[66:67]
	v_lshl_add_u64 v[66:67], v[130:131], 0, v[66:67]
	global_store_dword v[66:67], v74, off
	v_or_b32_e32 v66, 49, v132
	v_ashrrev_i32_e32 v67, 31, v66
	v_lshlrev_b64 v[66:67], 12, v[66:67]
	v_lshl_add_u64 v[66:67], v[130:131], 0, v[66:67]
	global_store_dword v[66:67], v75, off
	v_or_b32_e32 v66, 50, v132
	v_ashrrev_i32_e32 v67, 31, v66
	v_lshlrev_b64 v[66:67], 12, v[66:67]
	v_lshl_add_u64 v[66:67], v[130:131], 0, v[66:67]
	global_store_dword v[66:67], v76, off
	v_or_b32_e32 v66, 51, v132
	v_ashrrev_i32_e32 v67, 31, v66
	v_lshlrev_b64 v[66:67], 12, v[66:67]
	v_lshl_add_u64 v[66:67], v[130:131], 0, v[66:67]
	global_store_dword v[66:67], v77, off
	v_or_b32_e32 v66, 56, v132
	v_ashrrev_i32_e32 v67, 31, v66
	v_lshlrev_b64 v[66:67], 12, v[66:67]
	v_lshl_add_u64 v[66:67], v[130:131], 0, v[66:67]
	global_store_dword v[66:67], v78, off
	v_or_b32_e32 v66, 57, v132
	v_ashrrev_i32_e32 v67, 31, v66
	v_lshlrev_b64 v[66:67], 12, v[66:67]
	v_lshl_add_u64 v[66:67], v[130:131], 0, v[66:67]
	global_store_dword v[66:67], v79, off
	v_or_b32_e32 v66, 58, v132
	v_ashrrev_i32_e32 v67, 31, v66
	v_lshlrev_b64 v[66:67], 12, v[66:67]
	v_lshl_add_u64 v[66:67], v[130:131], 0, v[66:67]
	global_store_dword v[66:67], v80, off
	v_or_b32_e32 v66, 59, v132
	v_ashrrev_i32_e32 v67, 31, v66
	v_lshlrev_b64 v[66:67], 12, v[66:67]
	v_lshl_add_u64 v[66:67], v[130:131], 0, v[66:67]
	global_store_dword v[66:67], v81, off
	s_waitcnt lgkmcnt(0)
	s_and_saveexec_b64 s[8:9], s[0:1]
	v_mov_b32_e32 v66, s7
	ds_write_b32 v163, v66 offset:13324
	s_or_b64 exec, exec, s[8:9]
	ds_read_b32 v66, v163 offset:13320
	s_waitcnt lgkmcnt(0)
	v_cmp_lt_u32_e32 vcc, s34, v66
	s_cbranch_vccnz .LBB0_1556
	s_mov_b32 s4, 1
	s_branch .LBB0_1548

; __device__ __forceinline__ f32x16 mma32(bf16x8 a, bf16x8 b, f32x16 c) { return __builtin_amdgcn_mfma_f32_32x32x16_bf16(a, b, c, 0, 0, 0); }
; #define LDS_WAIT() asm volatile("s_waitcnt lgkmcnt(0)" ::: "memory")
; __device__ __forceinline__ void gla_scan_task(const P& p, int l, int s, int h, int sl, LAS unsigned char* ldsw, int lane) {
;     ...
; #pragma unroll
;         for (int d = 0; d < 4; ++d) {
; #pragma unroll
;             for (int ks = 0; ks < 4; ++ks) S[d] = mma32(FRAG16(bufB, d * 4 + ks, lane), vb[ks], S[d]);
; #pragma unroll
;             for (int g = 0; g < 4; ++g) { const f32x4v dc = FRAGF4(bufB, 16 + d * 4 + g, lane); S[d][4 * g] *= dc.x; S[d][4 * g + 1] *= dc.y; S[d][4 * g + 2] *= dc.z; S[d][4 * g + 3] *= dc.w; }
;         }
;         LDS_WAIT();
;         if (SCAN_LOADERS) { if (lane == 0) FL[4] = (unsigned)n + 1u; } else gla_issue_B(p, chn, bufB, r, hh);
.LBB0_1556:
	s_waitcnt lgkmcnt(0)
	v_add_u32_e32 v173, 0xf000, v209
	ds_read_b128 v[236:239], v209 offset:45056
	ds_read_b128 v[240:243], v209 offset:46080
	ds_read_b128 v[244:247], v209 offset:47104
	ds_read_b128 v[168:171], v209 offset:48128
	ds_read_b128 v[212:215], v209 offset:49152
	ds_read_b128 v[216:219], v209 offset:50176
	s_waitcnt lgkmcnt(5)
	v_mfma_f32_32x32x16_bf16 v[50:65], v[236:239], v[94:97], v[50:65]
	ds_read_b128 v[220:223], v209 offset:51200
	s_waitcnt lgkmcnt(5)
	v_mfma_f32_32x32x16_bf16 v[50:65], v[240:243], v[90:93], v[50:65]
	ds_read_b128 v[224:227], v209 offset:52224
	s_waitcnt lgkmcnt(5)
	v_mfma_f32_32x32x16_bf16 v[50:65], v[244:247], v[86:89], v[50:65]
	ds_read_b128 v[228:231], v209 offset:53248
	s_waitcnt lgkmcnt(5)
	v_mfma_f32_32x32x16_bf16 v[50:65], v[168:171], v[82:85], v[50:65]
	ds_read_b128 v[98:101], v173 offset:0
	ds_read_b128 v[74:77], v173 offset:1024
	ds_read_b128 v[70:73], v173 offset:2048
	ds_read_b128 v[66:69], v173 offset:3072
	ds_read_b128 v[232:235], v209 offset:54272
	s_waitcnt lgkmcnt(9)
	v_mfma_f32_32x32x16_bf16 v[34:49], v[212:215], v[94:97], v[34:49]
	ds_read_b128 v[236:239], v209 offset:55296
	s_waitcnt lgkmcnt(9)
	v_mfma_f32_32x32x16_bf16 v[34:49], v[216:219], v[90:93], v[34:49]
	ds_read_b128 v[240:243], v209 offset:56320
	s_waitcnt lgkmcnt(9)
	v_mfma_f32_32x32x16_bf16 v[34:49], v[220:223], v[86:89], v[34:49]
	ds_read_b128 v[244:247], v209 offset:57344
	s_waitcnt lgkmcnt(9)
	v_mfma_f32_32x32x16_bf16 v[34:49], v[224:227], v[82:85], v[34:49]
	ds_read_b128 v[110:113], v173 offset:4096
	ds_read_b128 v[106:109], v173 offset:5120
	ds_read_b128 v[102:105], v173 offset:6144
	ds_read_b128 v[78:81], v173 offset:7168
	ds_read_b128 v[168:171], v209 offset:58368
	s_waitcnt lgkmcnt(13)
	v_mfma_f32_32x32x16_bf16 v[18:33], v[228:231], v[94:97], v[18:33]
	ds_read_b128 v[212:215], v209 offset:59392
	s_waitcnt lgkmcnt(9)
	v_mfma_f32_32x32x16_bf16 v[18:33], v[232:235], v[90:93], v[18:33]
	ds_read_b128 v[216:219], v209 offset:60416
	s_waitcnt lgkmcnt(9)
	v_mfma_f32_32x32x16_bf16 v[18:33], v[236:239], v[86:89], v[18:33]
	s_waitcnt lgkmcnt(8)
	v_mfma_f32_32x32x16_bf16 v[18:33], v[240:243], v[82:85], v[18:33]
	ds_read_b128 v[126:129], v173 offset:8192
	ds_read_b128 v[122:125], v173 offset:9216
	ds_read_b128 v[118:121], v173 offset:10240
	ds_read_b128 v[114:117], v173 offset:11264
	s_waitcnt lgkmcnt(11)
	v_mfma_f32_32x32x16_bf16 v[2:17], v[244:247], v[94:97], v[2:17]
	s_waitcnt lgkmcnt(6)
	v_mfma_f32_32x32x16_bf16 v[2:17], v[168:171], v[90:93], v[2:17]
	s_waitcnt lgkmcnt(5)
	v_mfma_f32_32x32x16_bf16 v[2:17], v[212:215], v[86:89], v[2:17]
	s_waitcnt lgkmcnt(4)
	v_mfma_f32_32x32x16_bf16 v[2:17], v[216:219], v[82:85], v[2:17]
	ds_read_b128 v[90:93], v173 offset:12288
	ds_read_b128 v[94:97], v173 offset:13312
	ds_read_b128 v[82:85], v173 offset:14336
	ds_read_b128 v[86:89], v173 offset:15360
	s_waitcnt lgkmcnt(0)
	s_and_saveexec_b64 s[8:9], s[0:1]
	s_cbranch_execz .LBB0_1520
	v_mov_b32_e32 v132, s7
	ds_write_b32 v163, v132 offset:13328
	s_branch .LBB0_1520
